# P0: hand-written norm-row item and adaLN GEMV unit; work-queue pop returns asynchronously while the item runs
# baseline (speedup 1.0000x reference)
.LBB0_33:
	v_mov_b32_e32 v79, v0
	s_nop 0
	v_ashrrev_i32_e32 v81, 6, v79
	v_cmp_eq_u32_e64 s[4:5], 0, v79
	v_readfirstlane_b32 s29, v81
	s_and_saveexec_b64 s[6:7], s[4:5]
	v_mov_b32_e32 v2, s78
	ds_write_b32 v2, v1
	s_or_b64 exec, exec, s[6:7]
	s_waitcnt lgkmcnt(0)
	s_barrier
	ds_read_b32 v2, v72
	s_waitcnt lgkmcnt(0)
	v_readfirstlane_b32 s36, v2
	s_cmp_lt_i32 s36, s71
	s_cselect_b64 s[6:7], -1, 0
	s_and_b64 s[44:45], s[4:5], s[6:7]
	s_and_saveexec_b64 s[8:9], s[44:45]
	s_cbranch_execz .LBB0_39
	v_mov_b32_e32 v2, 1
	global_atomic_add v1, v67, v2, s[12:13] sc0

.Lnorm_lat:
	s_add_u32 s68, s60, 0x1000
	s_addc_u32 s69, s61, 0
	global_load_dwordx4 v[2:5], v66, s[56:57]
	global_load_dwordx4 v[6:9], v66, s[56:57] offset:1024
	global_load_dwordx4 v[10:13], v66, s[56:57] offset:2048
	global_load_dwordx4 v[14:17], v66, s[56:57] offset:3072
	global_load_dwordx4 v[18:21], v66, s[68:69]
	global_load_dwordx4 v[22:25], v66, s[68:69] offset:1024
	global_load_dwordx4 v[26:29], v66, s[68:69] offset:2048
	global_load_dwordx4 v[30:33], v66, s[68:69] offset:3072
	global_load_dwordx4 v[34:37], v66, s[60:61]
	global_load_dwordx4 v[38:41], v66, s[60:61] offset:1024
	global_load_dwordx4 v[42:45], v66, s[60:61] offset:2048
	global_load_dwordx4 v[46:49], v66, s[60:61] offset:3072
	global_load_dwordx4 v[106:109], v66, s[62:63] nt
	global_load_dwordx4 v[110:113], v66, s[62:63] offset:1024 nt
	global_load_dwordx4 v[114:117], v66, s[62:63] offset:2048 nt
	global_load_dwordx4 v[118:121], v66, s[62:63] offset:3072 nt
	s_add_u32 s62, s62, 0x1000
	s_addc_u32 s63, s63, 0
	global_load_dwordx4 v[122:125], v66, s[62:63] nt
	global_load_dwordx4 v[126:129], v66, s[62:63] offset:1024 nt
	global_load_dwordx4 v[130:133], v66, s[62:63] offset:2048 nt
	global_load_dwordx4 v[134:137], v66, s[62:63] offset:3072 nt
	s_add_u32 s62, s62, 0x1000
	s_addc_u32 s63, s63, 0
	global_load_dwordx4 v[138:141], v66, s[62:63] nt
	global_load_dwordx4 v[142:145], v66, s[62:63] offset:1024 nt
	global_load_dwordx4 v[146:149], v66, s[62:63] offset:2048 nt
	global_load_dwordx4 v[150:153], v66, s[62:63] offset:3072 nt
	s_add_u32 s62, s62, 0x1000
	s_addc_u32 s63, s63, 0
	global_load_dwordx4 v[154:157], v66, s[62:63] nt
	global_load_dwordx4 v[158:161], v66, s[62:63] offset:1024 nt
	global_load_dwordx4 v[162:165], v66, s[62:63] offset:2048 nt
	global_load_dwordx4 v[166:169], v66, s[62:63] offset:3072 nt
	s_add_u32 s62, s62, 0x1000
	s_addc_u32 s63, s63, 0
	global_load_dwordx4 v[170:173], v66, s[62:63] nt
	global_load_dwordx4 v[174:177], v66, s[62:63] offset:1024 nt
	global_load_dwordx4 v[178:181], v66, s[62:63] offset:2048 nt
	global_load_dwordx4 v[182:185], v66, s[62:63] offset:3072 nt
	s_add_u32 s62, s62, 0x1000
	s_addc_u32 s63, s63, 0
	global_load_dwordx4 v[186:189], v66, s[62:63] nt
	global_load_dwordx4 v[190:193], v66, s[62:63] offset:1024 nt
	global_load_dwordx4 v[194:197], v66, s[62:63] offset:2048 nt
	global_load_dwordx4 v[198:201], v66, s[62:63] offset:3072 nt
	s_add_u32 s62, s62, 0x1000
	s_addc_u32 s63, s63, 0
	global_load_dwordx4 v[202:205], v66, s[62:63] nt
	global_load_dwordx4 v[206:209], v66, s[62:63] offset:1024 nt
	global_load_dwordx4 v[210:213], v66, s[62:63] offset:2048 nt
	global_load_dwordx4 v[214:217], v66, s[62:63] offset:3072 nt
	s_add_u32 s62, s62, 0x1000
	s_addc_u32 s63, s63, 0
	global_load_dwordx4 v[218:221], v66, s[62:63] nt
	global_load_dwordx4 v[222:225], v66, s[62:63] offset:1024 nt
	global_load_dwordx4 v[226:229], v66, s[62:63] offset:2048 nt
	global_load_dwordx4 v[230:233], v66, s[62:63] offset:3072 nt
	s_waitcnt vmcnt(36)
	v_pk_add_f32 v[18:19], v[18:19], 1.0 op_sel_hi:[1,0]
	v_pk_add_f32 v[20:21], v[20:21], 1.0 op_sel_hi:[1,0]
	v_pk_add_f32 v[22:23], v[22:23], 1.0 op_sel_hi:[1,0]
	v_pk_add_f32 v[24:25], v[24:25], 1.0 op_sel_hi:[1,0]
	v_pk_add_f32 v[26:27], v[26:27], 1.0 op_sel_hi:[1,0]
	v_pk_add_f32 v[28:29], v[28:29], 1.0 op_sel_hi:[1,0]
	v_pk_add_f32 v[30:31], v[30:31], 1.0 op_sel_hi:[1,0]
	v_pk_add_f32 v[32:33], v[32:33], 1.0 op_sel_hi:[1,0]
	v_pk_mul_f32 v[2:3], v[2:3], v[18:19]
	v_pk_mul_f32 v[4:5], v[4:5], v[20:21]
	v_pk_mul_f32 v[6:7], v[6:7], v[22:23]
	v_pk_mul_f32 v[8:9], v[8:9], v[24:25]
	v_pk_mul_f32 v[10:11], v[10:11], v[26:27]
	v_pk_mul_f32 v[12:13], v[12:13], v[28:29]
	v_pk_mul_f32 v[14:15], v[14:15], v[30:31]
	v_pk_mul_f32 v[16:17], v[16:17], v[32:33]
	s_waitcnt vmcnt(16)
	v_pk_mul_f32 v[86:87], v[106:107], v[106:107]
	v_pk_mul_f32 v[88:89], v[108:109], v[108:109]
	v_pk_mul_f32 v[90:91], v[122:123], v[122:123]
	v_pk_mul_f32 v[92:93], v[124:125], v[124:125]
	v_pk_mul_f32 v[94:95], v[138:139], v[138:139]
	v_pk_mul_f32 v[96:97], v[140:141], v[140:141]
	v_pk_mul_f32 v[98:99], v[154:155], v[154:155]
	v_pk_mul_f32 v[100:101], v[156:157], v[156:157]
	v_pk_fma_f32 v[86:87], v[110:111], v[110:111], v[86:87]
	v_pk_fma_f32 v[88:89], v[112:113], v[112:113], v[88:89]
	v_pk_fma_f32 v[90:91], v[126:127], v[126:127], v[90:91]
	v_pk_fma_f32 v[92:93], v[128:129], v[128:129], v[92:93]
	v_pk_fma_f32 v[94:95], v[142:143], v[142:143], v[94:95]
	v_pk_fma_f32 v[96:97], v[144:145], v[144:145], v[96:97]
	v_pk_fma_f32 v[98:99], v[158:159], v[158:159], v[98:99]
	v_pk_fma_f32 v[100:101], v[160:161], v[160:161], v[100:101]
	v_pk_fma_f32 v[86:87], v[114:115], v[114:115], v[86:87]
	v_pk_fma_f32 v[88:89], v[116:117], v[116:117], v[88:89]
	v_pk_fma_f32 v[90:91], v[130:131], v[130:131], v[90:91]
	v_pk_fma_f32 v[92:93], v[132:133], v[132:133], v[92:93]
	v_pk_fma_f32 v[94:95], v[146:147], v[146:147], v[94:95]
	v_pk_fma_f32 v[96:97], v[148:149], v[148:149], v[96:97]
	v_pk_fma_f32 v[98:99], v[162:163], v[162:163], v[98:99]
	v_pk_fma_f32 v[100:101], v[164:165], v[164:165], v[100:101]
	v_pk_fma_f32 v[86:87], v[118:119], v[118:119], v[86:87]
	v_pk_fma_f32 v[88:89], v[120:121], v[120:121], v[88:89]
	v_pk_fma_f32 v[90:91], v[134:135], v[134:135], v[90:91]
	v_pk_fma_f32 v[92:93], v[136:137], v[136:137], v[92:93]
	v_pk_fma_f32 v[94:95], v[150:151], v[150:151], v[94:95]
	v_pk_fma_f32 v[96:97], v[152:153], v[152:153], v[96:97]
	v_pk_fma_f32 v[98:99], v[166:167], v[166:167], v[98:99]
	v_pk_fma_f32 v[100:101], v[168:169], v[168:169], v[100:101]
	v_pk_add_f32 v[86:87], v[86:87], v[88:89]
	v_pk_add_f32 v[90:91], v[90:91], v[92:93]
	v_pk_add_f32 v[94:95], v[94:95], v[96:97]
	v_pk_add_f32 v[98:99], v[98:99], v[100:101]
	v_add_f32_e32 v50, v86, v87
	v_add_f32_e32 v51, v90, v91
	v_add_f32_e32 v52, v94, v95
	v_add_f32_e32 v53, v98, v99
	v_add_f32_dpp v50, v50, v50 quad_perm:[1,0,3,2] row_mask:0xf bank_mask:0xf
	v_add_f32_dpp v51, v51, v51 quad_perm:[1,0,3,2] row_mask:0xf bank_mask:0xf
	v_add_f32_dpp v52, v52, v52 quad_perm:[1,0,3,2] row_mask:0xf bank_mask:0xf
	v_add_f32_dpp v53, v53, v53 quad_perm:[1,0,3,2] row_mask:0xf bank_mask:0xf
	v_add_f32_dpp v50, v50, v50 quad_perm:[2,3,0,1] row_mask:0xf bank_mask:0xf
	v_add_f32_dpp v51, v51, v51 quad_perm:[2,3,0,1] row_mask:0xf bank_mask:0xf
	v_add_f32_dpp v52, v52, v52 quad_perm:[2,3,0,1] row_mask:0xf bank_mask:0xf
	v_add_f32_dpp v53, v53, v53 quad_perm:[2,3,0,1] row_mask:0xf bank_mask:0xf
	v_add_f32_dpp v50, v50, v50 row_half_mirror row_mask:0xf bank_mask:0xf
	v_add_f32_dpp v51, v51, v51 row_half_mirror row_mask:0xf bank_mask:0xf
	v_add_f32_dpp v52, v52, v52 row_half_mirror row_mask:0xf bank_mask:0xf
	v_add_f32_dpp v53, v53, v53 row_half_mirror row_mask:0xf bank_mask:0xf
	v_add_f32_dpp v50, v50, v50 row_mirror row_mask:0xf bank_mask:0xf
	v_add_f32_dpp v51, v51, v51 row_mirror row_mask:0xf bank_mask:0xf
	v_add_f32_dpp v52, v52, v52 row_mirror row_mask:0xf bank_mask:0xf
	v_add_f32_dpp v53, v53, v53 row_mirror row_mask:0xf bank_mask:0xf
	v_add_f32_dpp v50, v50, v50 row_bcast:15 row_mask:0xa bank_mask:0xf
	v_add_f32_dpp v51, v51, v51 row_bcast:15 row_mask:0xa bank_mask:0xf
	v_add_f32_dpp v52, v52, v52 row_bcast:15 row_mask:0xa bank_mask:0xf
	v_add_f32_dpp v53, v53, v53 row_bcast:15 row_mask:0xa bank_mask:0xf
	v_add_f32_dpp v50, v50, v50 row_bcast:31 row_mask:0xc bank_mask:0xf
	v_add_f32_dpp v51, v51, v51 row_bcast:31 row_mask:0xc bank_mask:0xf
	v_add_f32_dpp v52, v52, v52 row_bcast:31 row_mask:0xc bank_mask:0xf
	v_add_f32_dpp v53, v53, v53 row_bcast:31 row_mask:0xc bank_mask:0xf
	v_readlane_b32 s52, v50, 63
	v_readlane_b32 s53, v51, 63
	v_readlane_b32 s54, v52, 63
	v_readlane_b32 s55, v53, 63
	v_mov_b32_e32 v60, s52
	v_mov_b32_e32 v62, s53
	v_mov_b32_e32 v64, s54
	v_mov_b32_e32 v84, s55
	v_fmamk_f32 v60, v60, 0x3a800000, v68
	v_fmamk_f32 v62, v62, 0x3a800000, v68
	v_fmamk_f32 v64, v64, 0x3a800000, v68
	v_fmamk_f32 v84, v84, 0x3a800000, v68
	v_rsq_f32_e32 v60, v60
	v_rsq_f32_e32 v62, v62
	v_rsq_f32_e32 v64, v64
	v_rsq_f32_e32 v84, v84
	v_pk_mul_f32 v[106:107], v[60:61], v[106:107] op_sel_hi:[0,1]
	v_pk_mul_f32 v[108:109], v[60:61], v[108:109] op_sel_hi:[0,1]
	v_pk_mul_f32 v[110:111], v[60:61], v[110:111] op_sel_hi:[0,1]
	v_pk_mul_f32 v[112:113], v[60:61], v[112:113] op_sel_hi:[0,1]
	v_pk_mul_f32 v[114:115], v[60:61], v[114:115] op_sel_hi:[0,1]
	v_pk_mul_f32 v[116:117], v[60:61], v[116:117] op_sel_hi:[0,1]
	v_pk_mul_f32 v[118:119], v[60:61], v[118:119] op_sel_hi:[0,1]
	v_pk_mul_f32 v[120:121], v[60:61], v[120:121] op_sel_hi:[0,1]
	v_pk_fma_f32 v[106:107], v[106:107], v[2:3], v[34:35]
	v_pk_fma_f32 v[108:109], v[108:109], v[4:5], v[36:37]
	v_pk_fma_f32 v[110:111], v[110:111], v[6:7], v[38:39]
	v_pk_fma_f32 v[112:113], v[112:113], v[8:9], v[40:41]
	v_pk_fma_f32 v[114:115], v[114:115], v[10:11], v[42:43]
	v_pk_fma_f32 v[116:117], v[116:117], v[12:13], v[44:45]
	v_pk_fma_f32 v[118:119], v[118:119], v[14:15], v[46:47]
	v_pk_fma_f32 v[120:121], v[120:121], v[16:17], v[48:49]
	v_cvt_pk_bf16_f32 v106, v106, v107
	v_cvt_pk_bf16_f32 v107, v108, v109
	v_cvt_pk_bf16_f32 v110, v110, v111
	v_cvt_pk_bf16_f32 v111, v112, v113
	v_cvt_pk_bf16_f32 v114, v114, v115
	v_cvt_pk_bf16_f32 v115, v116, v117
	v_cvt_pk_bf16_f32 v118, v118, v119
	v_cvt_pk_bf16_f32 v119, v120, v121
	global_store_dwordx2 v82, v[106:107], s[64:65]
	global_store_dwordx2 v82, v[110:111], s[64:65] offset:512
	global_store_dwordx2 v82, v[114:115], s[64:65] offset:1024
	global_store_dwordx2 v82, v[118:119], s[64:65] offset:1536
	s_add_u32 s64, s64, 0x800
	s_addc_u32 s65, s65, 0
	v_pk_mul_f32 v[122:123], v[62:63], v[122:123] op_sel_hi:[0,1]
	v_pk_mul_f32 v[124:125], v[62:63], v[124:125] op_sel_hi:[0,1]
	v_pk_mul_f32 v[126:127], v[62:63], v[126:127] op_sel_hi:[0,1]
	v_pk_mul_f32 v[128:129], v[62:63], v[128:129] op_sel_hi:[0,1]
	v_pk_mul_f32 v[130:131], v[62:63], v[130:131] op_sel_hi:[0,1]
	v_pk_mul_f32 v[132:133], v[62:63], v[132:133] op_sel_hi:[0,1]
	v_pk_mul_f32 v[134:135], v[62:63], v[134:135] op_sel_hi:[0,1]
	v_pk_mul_f32 v[136:137], v[62:63], v[136:137] op_sel_hi:[0,1]
	v_pk_fma_f32 v[122:123], v[122:123], v[2:3], v[34:35]
	v_pk_fma_f32 v[124:125], v[124:125], v[4:5], v[36:37]
	v_pk_fma_f32 v[126:127], v[126:127], v[6:7], v[38:39]
	v_pk_fma_f32 v[128:129], v[128:129], v[8:9], v[40:41]
	v_pk_fma_f32 v[130:131], v[130:131], v[10:11], v[42:43]
	v_pk_fma_f32 v[132:133], v[132:133], v[12:13], v[44:45]
	v_pk_fma_f32 v[134:135], v[134:135], v[14:15], v[46:47]
	v_pk_fma_f32 v[136:137], v[136:137], v[16:17], v[48:49]
	v_cvt_pk_bf16_f32 v122, v122, v123
	v_cvt_pk_bf16_f32 v123, v124, v125
	v_cvt_pk_bf16_f32 v126, v126, v127
	v_cvt_pk_bf16_f32 v127, v128, v129
	v_cvt_pk_bf16_f32 v130, v130, v131
	v_cvt_pk_bf16_f32 v131, v132, v133
	v_cvt_pk_bf16_f32 v134, v134, v135
	v_cvt_pk_bf16_f32 v135, v136, v137
	global_store_dwordx2 v82, v[122:123], s[64:65]
	global_store_dwordx2 v82, v[126:127], s[64:65] offset:512
	global_store_dwordx2 v82, v[130:131], s[64:65] offset:1024
	global_store_dwordx2 v82, v[134:135], s[64:65] offset:1536
	s_add_u32 s64, s64, 0x800
	s_addc_u32 s65, s65, 0
	v_pk_mul_f32 v[138:139], v[64:65], v[138:139] op_sel_hi:[0,1]
	v_pk_mul_f32 v[140:141], v[64:65], v[140:141] op_sel_hi:[0,1]
	v_pk_mul_f32 v[142:143], v[64:65], v[142:143] op_sel_hi:[0,1]
	v_pk_mul_f32 v[144:145], v[64:65], v[144:145] op_sel_hi:[0,1]
	v_pk_mul_f32 v[146:147], v[64:65], v[146:147] op_sel_hi:[0,1]
	v_pk_mul_f32 v[148:149], v[64:65], v[148:149] op_sel_hi:[0,1]
	v_pk_mul_f32 v[150:151], v[64:65], v[150:151] op_sel_hi:[0,1]
	v_pk_mul_f32 v[152:153], v[64:65], v[152:153] op_sel_hi:[0,1]
	v_pk_fma_f32 v[138:139], v[138:139], v[2:3], v[34:35]
	v_pk_fma_f32 v[140:141], v[140:141], v[4:5], v[36:37]
	v_pk_fma_f32 v[142:143], v[142:143], v[6:7], v[38:39]
	v_pk_fma_f32 v[144:145], v[144:145], v[8:9], v[40:41]
	v_pk_fma_f32 v[146:147], v[146:147], v[10:11], v[42:43]
	v_pk_fma_f32 v[148:149], v[148:149], v[12:13], v[44:45]
	v_pk_fma_f32 v[150:151], v[150:151], v[14:15], v[46:47]
	v_pk_fma_f32 v[152:153], v[152:153], v[16:17], v[48:49]
	v_cvt_pk_bf16_f32 v138, v138, v139
	v_cvt_pk_bf16_f32 v139, v140, v141
	v_cvt_pk_bf16_f32 v142, v142, v143
	v_cvt_pk_bf16_f32 v143, v144, v145
	v_cvt_pk_bf16_f32 v146, v146, v147
	v_cvt_pk_bf16_f32 v147, v148, v149
	v_cvt_pk_bf16_f32 v150, v150, v151
	v_cvt_pk_bf16_f32 v151, v152, v153
	global_store_dwordx2 v82, v[138:139], s[64:65]
	global_store_dwordx2 v82, v[142:143], s[64:65] offset:512
	global_store_dwordx2 v82, v[146:147], s[64:65] offset:1024
	global_store_dwordx2 v82, v[150:151], s[64:65] offset:1536
	s_add_u32 s64, s64, 0x800
	s_addc_u32 s65, s65, 0
	v_pk_mul_f32 v[154:155], v[84:85], v[154:155] op_sel_hi:[0,1]
	v_pk_mul_f32 v[156:157], v[84:85], v[156:157] op_sel_hi:[0,1]
	v_pk_mul_f32 v[158:159], v[84:85], v[158:159] op_sel_hi:[0,1]
	v_pk_mul_f32 v[160:161], v[84:85], v[160:161] op_sel_hi:[0,1]
	v_pk_mul_f32 v[162:163], v[84:85], v[162:163] op_sel_hi:[0,1]
	v_pk_mul_f32 v[164:165], v[84:85], v[164:165] op_sel_hi:[0,1]
	v_pk_mul_f32 v[166:167], v[84:85], v[166:167] op_sel_hi:[0,1]
	v_pk_mul_f32 v[168:169], v[84:85], v[168:169] op_sel_hi:[0,1]
	v_pk_fma_f32 v[154:155], v[154:155], v[2:3], v[34:35]
	v_pk_fma_f32 v[156:157], v[156:157], v[4:5], v[36:37]
	v_pk_fma_f32 v[158:159], v[158:159], v[6:7], v[38:39]
	v_pk_fma_f32 v[160:161], v[160:161], v[8:9], v[40:41]
	v_pk_fma_f32 v[162:163], v[162:163], v[10:11], v[42:43]
	v_pk_fma_f32 v[164:165], v[164:165], v[12:13], v[44:45]
	v_pk_fma_f32 v[166:167], v[166:167], v[14:15], v[46:47]
	v_pk_fma_f32 v[168:169], v[168:169], v[16:17], v[48:49]
	v_cvt_pk_bf16_f32 v154, v154, v155
	v_cvt_pk_bf16_f32 v155, v156, v157
	v_cvt_pk_bf16_f32 v158, v158, v159
	v_cvt_pk_bf16_f32 v159, v160, v161
	v_cvt_pk_bf16_f32 v162, v162, v163
	v_cvt_pk_bf16_f32 v163, v164, v165
	v_cvt_pk_bf16_f32 v166, v166, v167
	v_cvt_pk_bf16_f32 v167, v168, v169
	global_store_dwordx2 v82, v[154:155], s[64:65]
	global_store_dwordx2 v82, v[158:159], s[64:65] offset:512
	global_store_dwordx2 v82, v[162:163], s[64:65] offset:1024
	global_store_dwordx2 v82, v[166:167], s[64:65] offset:1536
	s_add_u32 s64, s64, 0x800
	s_addc_u32 s65, s65, 0
	s_waitcnt vmcnt(16)
	v_pk_mul_f32 v[86:87], v[170:171], v[170:171]
	v_pk_mul_f32 v[88:89], v[172:173], v[172:173]
	v_pk_mul_f32 v[90:91], v[186:187], v[186:187]
	v_pk_mul_f32 v[92:93], v[188:189], v[188:189]
	v_pk_mul_f32 v[94:95], v[202:203], v[202:203]
	v_pk_mul_f32 v[96:97], v[204:205], v[204:205]
	v_pk_mul_f32 v[98:99], v[218:219], v[218:219]
	v_pk_mul_f32 v[100:101], v[220:221], v[220:221]
	v_pk_fma_f32 v[86:87], v[174:175], v[174:175], v[86:87]
	v_pk_fma_f32 v[88:89], v[176:177], v[176:177], v[88:89]
	v_pk_fma_f32 v[90:91], v[190:191], v[190:191], v[90:91]
	v_pk_fma_f32 v[92:93], v[192:193], v[192:193], v[92:93]
	v_pk_fma_f32 v[94:95], v[206:207], v[206:207], v[94:95]
	v_pk_fma_f32 v[96:97], v[208:209], v[208:209], v[96:97]
	v_pk_fma_f32 v[98:99], v[222:223], v[222:223], v[98:99]
	v_pk_fma_f32 v[100:101], v[224:225], v[224:225], v[100:101]
	v_pk_fma_f32 v[86:87], v[178:179], v[178:179], v[86:87]
	v_pk_fma_f32 v[88:89], v[180:181], v[180:181], v[88:89]
	v_pk_fma_f32 v[90:91], v[194:195], v[194:195], v[90:91]
	v_pk_fma_f32 v[92:93], v[196:197], v[196:197], v[92:93]
	v_pk_fma_f32 v[94:95], v[210:211], v[210:211], v[94:95]
	v_pk_fma_f32 v[96:97], v[212:213], v[212:213], v[96:97]
	v_pk_fma_f32 v[98:99], v[226:227], v[226:227], v[98:99]
	v_pk_fma_f32 v[100:101], v[228:229], v[228:229], v[100:101]
	v_pk_fma_f32 v[86:87], v[182:183], v[182:183], v[86:87]
	v_pk_fma_f32 v[88:89], v[184:185], v[184:185], v[88:89]
	v_pk_fma_f32 v[90:91], v[198:199], v[198:199], v[90:91]
	v_pk_fma_f32 v[92:93], v[200:201], v[200:201], v[92:93]
	v_pk_fma_f32 v[94:95], v[214:215], v[214:215], v[94:95]
	v_pk_fma_f32 v[96:97], v[216:217], v[216:217], v[96:97]
	v_pk_fma_f32 v[98:99], v[230:231], v[230:231], v[98:99]
	v_pk_fma_f32 v[100:101], v[232:233], v[232:233], v[100:101]
	v_pk_add_f32 v[86:87], v[86:87], v[88:89]
	v_pk_add_f32 v[90:91], v[90:91], v[92:93]
	v_pk_add_f32 v[94:95], v[94:95], v[96:97]
	v_pk_add_f32 v[98:99], v[98:99], v[100:101]
	v_add_f32_e32 v50, v86, v87
	v_add_f32_e32 v51, v90, v91
	v_add_f32_e32 v52, v94, v95
	v_add_f32_e32 v53, v98, v99
	v_add_f32_dpp v50, v50, v50 quad_perm:[1,0,3,2] row_mask:0xf bank_mask:0xf
	v_add_f32_dpp v51, v51, v51 quad_perm:[1,0,3,2] row_mask:0xf bank_mask:0xf
	v_add_f32_dpp v52, v52, v52 quad_perm:[1,0,3,2] row_mask:0xf bank_mask:0xf
	v_add_f32_dpp v53, v53, v53 quad_perm:[1,0,3,2] row_mask:0xf bank_mask:0xf
	v_add_f32_dpp v50, v50, v50 quad_perm:[2,3,0,1] row_mask:0xf bank_mask:0xf
	v_add_f32_dpp v51, v51, v51 quad_perm:[2,3,0,1] row_mask:0xf bank_mask:0xf
	v_add_f32_dpp v52, v52, v52 quad_perm:[2,3,0,1] row_mask:0xf bank_mask:0xf
	v_add_f32_dpp v53, v53, v53 quad_perm:[2,3,0,1] row_mask:0xf bank_mask:0xf
	v_add_f32_dpp v50, v50, v50 row_half_mirror row_mask:0xf bank_mask:0xf
	v_add_f32_dpp v51, v51, v51 row_half_mirror row_mask:0xf bank_mask:0xf
	v_add_f32_dpp v52, v52, v52 row_half_mirror row_mask:0xf bank_mask:0xf
	v_add_f32_dpp v53, v53, v53 row_half_mirror row_mask:0xf bank_mask:0xf
	v_add_f32_dpp v50, v50, v50 row_mirror row_mask:0xf bank_mask:0xf
	v_add_f32_dpp v51, v51, v51 row_mirror row_mask:0xf bank_mask:0xf
	v_add_f32_dpp v52, v52, v52 row_mirror row_mask:0xf bank_mask:0xf
	v_add_f32_dpp v53, v53, v53 row_mirror row_mask:0xf bank_mask:0xf
	v_add_f32_dpp v50, v50, v50 row_bcast:15 row_mask:0xa bank_mask:0xf
	v_add_f32_dpp v51, v51, v51 row_bcast:15 row_mask:0xa bank_mask:0xf
	v_add_f32_dpp v52, v52, v52 row_bcast:15 row_mask:0xa bank_mask:0xf
	v_add_f32_dpp v53, v53, v53 row_bcast:15 row_mask:0xa bank_mask:0xf
	v_add_f32_dpp v50, v50, v50 row_bcast:31 row_mask:0xc bank_mask:0xf
	v_add_f32_dpp v51, v51, v51 row_bcast:31 row_mask:0xc bank_mask:0xf
	v_add_f32_dpp v52, v52, v52 row_bcast:31 row_mask:0xc bank_mask:0xf
	v_add_f32_dpp v53, v53, v53 row_bcast:31 row_mask:0xc bank_mask:0xf
	v_readlane_b32 s52, v50, 63
	v_readlane_b32 s53, v51, 63
	v_readlane_b32 s54, v52, 63
	v_readlane_b32 s55, v53, 63
	v_mov_b32_e32 v60, s52
	v_mov_b32_e32 v62, s53
	v_mov_b32_e32 v64, s54
	v_mov_b32_e32 v84, s55
	v_fmamk_f32 v60, v60, 0x3a800000, v68
	v_fmamk_f32 v62, v62, 0x3a800000, v68
	v_fmamk_f32 v64, v64, 0x3a800000, v68
	v_fmamk_f32 v84, v84, 0x3a800000, v68
	v_rsq_f32_e32 v60, v60
	v_rsq_f32_e32 v62, v62
	v_rsq_f32_e32 v64, v64
	v_rsq_f32_e32 v84, v84
	v_pk_mul_f32 v[170:171], v[60:61], v[170:171] op_sel_hi:[0,1]
	v_pk_mul_f32 v[172:173], v[60:61], v[172:173] op_sel_hi:[0,1]
	v_pk_mul_f32 v[174:175], v[60:61], v[174:175] op_sel_hi:[0,1]
	v_pk_mul_f32 v[176:177], v[60:61], v[176:177] op_sel_hi:[0,1]
	v_pk_mul_f32 v[178:179], v[60:61], v[178:179] op_sel_hi:[0,1]
	v_pk_mul_f32 v[180:181], v[60:61], v[180:181] op_sel_hi:[0,1]
	v_pk_mul_f32 v[182:183], v[60:61], v[182:183] op_sel_hi:[0,1]
	v_pk_mul_f32 v[184:185], v[60:61], v[184:185] op_sel_hi:[0,1]
	v_pk_fma_f32 v[170:171], v[170:171], v[2:3], v[34:35]
	v_pk_fma_f32 v[172:173], v[172:173], v[4:5], v[36:37]
	v_pk_fma_f32 v[174:175], v[174:175], v[6:7], v[38:39]
	v_pk_fma_f32 v[176:177], v[176:177], v[8:9], v[40:41]
	v_pk_fma_f32 v[178:179], v[178:179], v[10:11], v[42:43]
	v_pk_fma_f32 v[180:181], v[180:181], v[12:13], v[44:45]
	v_pk_fma_f32 v[182:183], v[182:183], v[14:15], v[46:47]
	v_pk_fma_f32 v[184:185], v[184:185], v[16:17], v[48:49]
	v_cvt_pk_bf16_f32 v170, v170, v171
	v_cvt_pk_bf16_f32 v171, v172, v173
	v_cvt_pk_bf16_f32 v174, v174, v175
	v_cvt_pk_bf16_f32 v175, v176, v177
	v_cvt_pk_bf16_f32 v178, v178, v179
	v_cvt_pk_bf16_f32 v179, v180, v181
	v_cvt_pk_bf16_f32 v182, v182, v183
	v_cvt_pk_bf16_f32 v183, v184, v185
	global_store_dwordx2 v82, v[170:171], s[64:65]
	global_store_dwordx2 v82, v[174:175], s[64:65] offset:512
	global_store_dwordx2 v82, v[178:179], s[64:65] offset:1024
	global_store_dwordx2 v82, v[182:183], s[64:65] offset:1536
	s_add_u32 s64, s64, 0x800
	s_addc_u32 s65, s65, 0
	v_pk_mul_f32 v[186:187], v[62:63], v[186:187] op_sel_hi:[0,1]
	v_pk_mul_f32 v[188:189], v[62:63], v[188:189] op_sel_hi:[0,1]
	v_pk_mul_f32 v[190:191], v[62:63], v[190:191] op_sel_hi:[0,1]
	v_pk_mul_f32 v[192:193], v[62:63], v[192:193] op_sel_hi:[0,1]
	v_pk_mul_f32 v[194:195], v[62:63], v[194:195] op_sel_hi:[0,1]
	v_pk_mul_f32 v[196:197], v[62:63], v[196:197] op_sel_hi:[0,1]
	v_pk_mul_f32 v[198:199], v[62:63], v[198:199] op_sel_hi:[0,1]
	v_pk_mul_f32 v[200:201], v[62:63], v[200:201] op_sel_hi:[0,1]
	v_pk_fma_f32 v[186:187], v[186:187], v[2:3], v[34:35]
	v_pk_fma_f32 v[188:189], v[188:189], v[4:5], v[36:37]
	v_pk_fma_f32 v[190:191], v[190:191], v[6:7], v[38:39]
	v_pk_fma_f32 v[192:193], v[192:193], v[8:9], v[40:41]
	v_pk_fma_f32 v[194:195], v[194:195], v[10:11], v[42:43]
	v_pk_fma_f32 v[196:197], v[196:197], v[12:13], v[44:45]
	v_pk_fma_f32 v[198:199], v[198:199], v[14:15], v[46:47]
	v_pk_fma_f32 v[200:201], v[200:201], v[16:17], v[48:49]
	v_cvt_pk_bf16_f32 v186, v186, v187
	v_cvt_pk_bf16_f32 v187, v188, v189
	v_cvt_pk_bf16_f32 v190, v190, v191
	v_cvt_pk_bf16_f32 v191, v192, v193
	v_cvt_pk_bf16_f32 v194, v194, v195
	v_cvt_pk_bf16_f32 v195, v196, v197
	v_cvt_pk_bf16_f32 v198, v198, v199
	v_cvt_pk_bf16_f32 v199, v200, v201
	global_store_dwordx2 v82, v[186:187], s[64:65]
	global_store_dwordx2 v82, v[190:191], s[64:65] offset:512
	global_store_dwordx2 v82, v[194:195], s[64:65] offset:1024
	global_store_dwordx2 v82, v[198:199], s[64:65] offset:1536
	s_add_u32 s64, s64, 0x800
	s_addc_u32 s65, s65, 0
	v_pk_mul_f32 v[202:203], v[64:65], v[202:203] op_sel_hi:[0,1]
	v_pk_mul_f32 v[204:205], v[64:65], v[204:205] op_sel_hi:[0,1]
	v_pk_mul_f32 v[206:207], v[64:65], v[206:207] op_sel_hi:[0,1]
	v_pk_mul_f32 v[208:209], v[64:65], v[208:209] op_sel_hi:[0,1]
	v_pk_mul_f32 v[210:211], v[64:65], v[210:211] op_sel_hi:[0,1]
	v_pk_mul_f32 v[212:213], v[64:65], v[212:213] op_sel_hi:[0,1]
	v_pk_mul_f32 v[214:215], v[64:65], v[214:215] op_sel_hi:[0,1]
	v_pk_mul_f32 v[216:217], v[64:65], v[216:217] op_sel_hi:[0,1]
	v_pk_fma_f32 v[202:203], v[202:203], v[2:3], v[34:35]
	v_pk_fma_f32 v[204:205], v[204:205], v[4:5], v[36:37]
	v_pk_fma_f32 v[206:207], v[206:207], v[6:7], v[38:39]
	v_pk_fma_f32 v[208:209], v[208:209], v[8:9], v[40:41]
	v_pk_fma_f32 v[210:211], v[210:211], v[10:11], v[42:43]
	v_pk_fma_f32 v[212:213], v[212:213], v[12:13], v[44:45]
	v_pk_fma_f32 v[214:215], v[214:215], v[14:15], v[46:47]
	v_pk_fma_f32 v[216:217], v[216:217], v[16:17], v[48:49]
	v_cvt_pk_bf16_f32 v202, v202, v203
	v_cvt_pk_bf16_f32 v203, v204, v205
	v_cvt_pk_bf16_f32 v206, v206, v207
	v_cvt_pk_bf16_f32 v207, v208, v209
	v_cvt_pk_bf16_f32 v210, v210, v211
	v_cvt_pk_bf16_f32 v211, v212, v213
	v_cvt_pk_bf16_f32 v214, v214, v215
	v_cvt_pk_bf16_f32 v215, v216, v217
	global_store_dwordx2 v82, v[202:203], s[64:65]
	global_store_dwordx2 v82, v[206:207], s[64:65] offset:512
	global_store_dwordx2 v82, v[210:211], s[64:65] offset:1024
	global_store_dwordx2 v82, v[214:215], s[64:65] offset:1536
	s_add_u32 s64, s64, 0x800
	s_addc_u32 s65, s65, 0
	v_pk_mul_f32 v[218:219], v[84:85], v[218:219] op_sel_hi:[0,1]
	v_pk_mul_f32 v[220:221], v[84:85], v[220:221] op_sel_hi:[0,1]
	v_pk_mul_f32 v[222:223], v[84:85], v[222:223] op_sel_hi:[0,1]
	v_pk_mul_f32 v[224:225], v[84:85], v[224:225] op_sel_hi:[0,1]
	v_pk_mul_f32 v[226:227], v[84:85], v[226:227] op_sel_hi:[0,1]
	v_pk_mul_f32 v[228:229], v[84:85], v[228:229] op_sel_hi:[0,1]
	v_pk_mul_f32 v[230:231], v[84:85], v[230:231] op_sel_hi:[0,1]
	v_pk_mul_f32 v[232:233], v[84:85], v[232:233] op_sel_hi:[0,1]
	v_pk_fma_f32 v[218:219], v[218:219], v[2:3], v[34:35]
	v_pk_fma_f32 v[220:221], v[220:221], v[4:5], v[36:37]
	v_pk_fma_f32 v[222:223], v[222:223], v[6:7], v[38:39]
	v_pk_fma_f32 v[224:225], v[224:225], v[8:9], v[40:41]
	v_pk_fma_f32 v[226:227], v[226:227], v[10:11], v[42:43]
	v_pk_fma_f32 v[228:229], v[228:229], v[12:13], v[44:45]
	v_pk_fma_f32 v[230:231], v[230:231], v[14:15], v[46:47]
	v_pk_fma_f32 v[232:233], v[232:233], v[16:17], v[48:49]
	v_cvt_pk_bf16_f32 v218, v218, v219
	v_cvt_pk_bf16_f32 v219, v220, v221
	v_cvt_pk_bf16_f32 v222, v222, v223
	v_cvt_pk_bf16_f32 v223, v224, v225
	v_cvt_pk_bf16_f32 v226, v226, v227
	v_cvt_pk_bf16_f32 v227, v228, v229
	v_cvt_pk_bf16_f32 v230, v230, v231
	v_cvt_pk_bf16_f32 v231, v232, v233
	global_store_dwordx2 v82, v[218:219], s[64:65]
	global_store_dwordx2 v82, v[222:223], s[64:65] offset:512
	global_store_dwordx2 v82, v[226:227], s[64:65] offset:1024
	global_store_dwordx2 v82, v[230:231], s[64:65] offset:1536
	s_add_u32 s64, s64, 0x800
	s_addc_u32 s65, s65, 0
	s_mov_b32 s68, 0x2aaaaaab
	s_mov_b64 s[52:53], 0

.LBB0_76:
	s_load_dwordx2 s[54:55], s[0:1], 0x8
	s_load_dwordx2 s[56:57], s[0:1], 0x18
	s_load_dwordx2 s[58:59], s[0:1], 0x20
	s_load_dwordx2 s[8:9], s[0:1], 0x28
	s_add_i32 s36, s44, 0xffffff40
	s_and_b32 s45, s36, 63
	s_mulk_i32 s45, 0x60
	s_lshr_b32 s52, s36, 6
	s_lshl_b32 s60, s52, 8
	s_mov_b32 s53, 0x2aaaaaab
	v_and_b32_e32 v6, 0xff, v79
	v_lshrrev_b32_e32 v7, 8, v79
	v_lshl_add_u32 v6, v7, 10, v6
	v_add_u32_e32 v6, s60, v6
	v_lshlrev_b32_e32 v6, 2, v6
	v_add_u32_e32 v7, s60, v79
	v_lshlrev_b32_e32 v7, 2, v7
	v_mul_hi_u32 v2, v79, s53
	v_lshrrev_b32_e32 v2, 2, v2
	v_mul_u32_u24_e32 v3, 24, v2
	v_sub_u32_e32 v3, v79, v3
	v_add_u32_e32 v4, s60, v2
	v_mul_u32_u24_e32 v4, 0x1800, v4
	v_lshl_add_u32 v5, v3, 2, s45
	v_add_lshl_u32 v4, v4, v5, 2
	v_lshrrev_b32_e32 v11, 2, v2
	v_mul_u32_u24_e32 v12, 0x60, v11
	v_sub_u32_e32 v12, v79, v12
	v_add_u32_e32 v13, s45, v12
	v_lshlrev_b32_e32 v14, 2, v13
	s_waitcnt lgkmcnt(0)
	global_load_dword v8, v6, s[54:55]
	v_cmp_gt_u32_e32 vcc, 0x100, v79
	s_and_saveexec_b64 s[4:5], vcc
	global_load_dword v9, v7, s[56:57]
	s_mov_b64 exec, s[4:5]
	v_cmp_gt_u32_e32 vcc, 0x180, v79
	s_and_saveexec_b64 s[4:5], vcc
	s_cbranch_execz .Lgemv_now
	global_load_dwordx4 v[106:109], v4, s[58:59] nt
	v_add_u32_e32 v10, 0x60000, v4
	global_load_dwordx4 v[110:113], v10, s[58:59] nt
	v_add_u32_e32 v10, 0xc0000, v4
	global_load_dwordx4 v[114:117], v10, s[58:59] nt
	v_add_u32_e32 v10, 0x120000, v4
	global_load_dwordx4 v[118:121], v10, s[58:59] nt
	v_add_u32_e32 v10, 0x180000, v4
	global_load_dwordx4 v[122:125], v10, s[58:59] nt
	v_add_u32_e32 v10, 0x1e0000, v4
	global_load_dwordx4 v[126:129], v10, s[58:59] nt
	v_add_u32_e32 v10, 0x240000, v4
	global_load_dwordx4 v[130:133], v10, s[58:59] nt
	v_add_u32_e32 v10, 0x2a0000, v4
	global_load_dwordx4 v[134:137], v10, s[58:59] nt
	v_add_u32_e32 v10, 0x300000, v4
	global_load_dwordx4 v[138:141], v10, s[58:59] nt
	v_add_u32_e32 v10, 0x360000, v4
	global_load_dwordx4 v[142:145], v10, s[58:59] nt
	v_add_u32_e32 v10, 0x3c0000, v4
	global_load_dwordx4 v[146:149], v10, s[58:59] nt
	v_add_u32_e32 v10, 0x420000, v4
	global_load_dwordx4 v[150:153], v10, s[58:59] nt
	v_add_u32_e32 v10, 0x480000, v4
	global_load_dwordx4 v[154:157], v10, s[58:59] nt
	v_add_u32_e32 v10, 0x4e0000, v4
	global_load_dwordx4 v[158:161], v10, s[58:59] nt
	v_add_u32_e32 v10, 0x540000, v4
	global_load_dwordx4 v[162:165], v10, s[58:59] nt
	v_add_u32_e32 v10, 0x5a0000, v4
	global_load_dwordx4 v[166:169], v10, s[58:59] nt
.Lgemv_now:
	s_mov_b64 exec, s[4:5]
	v_cmp_gt_u32_e32 vcc, 0x120, v79
	s_and_saveexec_b64 s[4:5], vcc
	global_load_dword v230, v14, s[8:9]
	s_mov_b64 exec, s[4:5]
	v_lshlrev_b32_e32 v16, 2, v79
	s_waitcnt vmcnt(0)
	v_mul_f32_e32 v15, 0xbfb8aa3b, v8
	v_exp_f32_e32 v15, v15
	s_nop 0
	v_add_f32_e32 v15, 1.0, v15
	v_rcp_f32_e32 v15, v15
	s_nop 0
	v_mul_f32_e32 v8, v8, v15
	ds_write_b32 v16, v8
	v_cmp_gt_u32_e32 vcc, 0x100, v79
	s_and_saveexec_b64 s[4:5], vcc
	v_mul_f32_e32 v15, 0xbfb8aa3b, v9
	v_exp_f32_e32 v15, v15
	s_nop 0
	v_add_f32_e32 v15, 1.0, v15
	v_rcp_f32_e32 v15, v15
	s_nop 0
	v_mul_f32_e32 v9, v9, v15
	ds_write_b32 v16, v9 offset:2048
	s_mov_b64 exec, s[4:5]
	s_waitcnt lgkmcnt(0)
	s_barrier
	v_cmp_gt_u32_e32 vcc, 0x180, v79
	s_and_saveexec_b64 s[4:5], vcc
	s_cbranch_execz .Lgemv_nofma
	v_lshlrev_b32_e32 v17, 2, v2
	v_add_u32_e32 v18, 0x400, v17
	v_add_u32_e32 v19, 0x800, v17
	ds_read2_b32 v[170:171], v17 offset0:0 offset1:16
	ds_read2_b32 v[172:173], v17 offset0:32 offset1:48
	ds_read2_b32 v[174:175], v17 offset0:64 offset1:80
	ds_read2_b32 v[176:177], v17 offset0:96 offset1:112
	ds_read2_b32 v[178:179], v17 offset0:128 offset1:144
	ds_read2_b32 v[180:181], v17 offset0:160 offset1:176
	ds_read2_b32 v[182:183], v17 offset0:192 offset1:208
	ds_read2_b32 v[184:185], v17 offset0:224 offset1:240
	ds_read2_b32 v[186:187], v18 offset0:0 offset1:16
	ds_read2_b32 v[188:189], v18 offset0:32 offset1:48
	ds_read2_b32 v[190:191], v18 offset0:64 offset1:80
	ds_read2_b32 v[192:193], v18 offset0:96 offset1:112
	ds_read2_b32 v[194:195], v18 offset0:128 offset1:144
	ds_read2_b32 v[196:197], v18 offset0:160 offset1:176
	ds_read2_b32 v[198:199], v18 offset0:192 offset1:208
	ds_read2_b32 v[200:201], v18 offset0:224 offset1:240
	ds_read2_b32 v[202:203], v19 offset0:0 offset1:16
	ds_read2_b32 v[204:205], v19 offset0:32 offset1:48
	ds_read2_b32 v[206:207], v19 offset0:64 offset1:80
	ds_read2_b32 v[208:209], v19 offset0:96 offset1:112
	ds_read2_b32 v[210:211], v19 offset0:128 offset1:144
	ds_read2_b32 v[212:213], v19 offset0:160 offset1:176
	ds_read2_b32 v[214:215], v19 offset0:192 offset1:208
	ds_read2_b32 v[216:217], v19 offset0:224 offset1:240
	v_mov_b32_e32 v218, 0
	v_mov_b32_e32 v219, 0
	v_mov_b32_e32 v220, 0
	v_mov_b32_e32 v221, 0
	v_mov_b32_e32 v222, 0
	v_mov_b32_e32 v223, 0
	v_mov_b32_e32 v224, 0
	v_mov_b32_e32 v225, 0
	v_mov_b32_e32 v226, 0
	v_mov_b32_e32 v227, 0
	v_mov_b32_e32 v228, 0
	v_mov_b32_e32 v229, 0
	s_waitcnt lgkmcnt(0)
	v_fmac_f32_e32 v218, v106, v170
	v_fmac_f32_e32 v219, v107, v170
	v_fmac_f32_e32 v220, v108, v170
	v_fmac_f32_e32 v221, v109, v170
	v_fmac_f32_e32 v222, v106, v186
	v_fmac_f32_e32 v223, v107, v186
	v_fmac_f32_e32 v224, v108, v186
	v_fmac_f32_e32 v225, v109, v186
	v_fmac_f32_e32 v226, v106, v202
	v_fmac_f32_e32 v227, v107, v202
	v_fmac_f32_e32 v228, v108, v202
	v_fmac_f32_e32 v229, v109, v202
	v_fmac_f32_e32 v218, v110, v171
	v_fmac_f32_e32 v219, v111, v171
	v_fmac_f32_e32 v220, v112, v171
	v_fmac_f32_e32 v221, v113, v171
	v_fmac_f32_e32 v222, v110, v187
	v_fmac_f32_e32 v223, v111, v187
	v_fmac_f32_e32 v224, v112, v187
	v_fmac_f32_e32 v225, v113, v187
	v_fmac_f32_e32 v226, v110, v203
	v_fmac_f32_e32 v227, v111, v203
	v_fmac_f32_e32 v228, v112, v203
	v_fmac_f32_e32 v229, v113, v203
	v_fmac_f32_e32 v218, v114, v172
	v_fmac_f32_e32 v219, v115, v172
	v_fmac_f32_e32 v220, v116, v172
	v_fmac_f32_e32 v221, v117, v172
	v_fmac_f32_e32 v222, v114, v188
	v_fmac_f32_e32 v223, v115, v188
	v_fmac_f32_e32 v224, v116, v188
	v_fmac_f32_e32 v225, v117, v188
	v_fmac_f32_e32 v226, v114, v204
	v_fmac_f32_e32 v227, v115, v204
	v_fmac_f32_e32 v228, v116, v204
	v_fmac_f32_e32 v229, v117, v204
	v_fmac_f32_e32 v218, v118, v173
	v_fmac_f32_e32 v219, v119, v173
	v_fmac_f32_e32 v220, v120, v173
	v_fmac_f32_e32 v221, v121, v173
	v_fmac_f32_e32 v222, v118, v189
	v_fmac_f32_e32 v223, v119, v189
	v_fmac_f32_e32 v224, v120, v189
	v_fmac_f32_e32 v225, v121, v189
	v_fmac_f32_e32 v226, v118, v205
	v_fmac_f32_e32 v227, v119, v205
	v_fmac_f32_e32 v228, v120, v205
	v_fmac_f32_e32 v229, v121, v205
	v_fmac_f32_e32 v218, v122, v174
	v_fmac_f32_e32 v219, v123, v174
	v_fmac_f32_e32 v220, v124, v174
	v_fmac_f32_e32 v221, v125, v174
	v_fmac_f32_e32 v222, v122, v190
	v_fmac_f32_e32 v223, v123, v190
	v_fmac_f32_e32 v224, v124, v190
	v_fmac_f32_e32 v225, v125, v190
	v_fmac_f32_e32 v226, v122, v206
	v_fmac_f32_e32 v227, v123, v206
	v_fmac_f32_e32 v228, v124, v206
	v_fmac_f32_e32 v229, v125, v206
	v_fmac_f32_e32 v218, v126, v175
	v_fmac_f32_e32 v219, v127, v175
	v_fmac_f32_e32 v220, v128, v175
	v_fmac_f32_e32 v221, v129, v175
	v_fmac_f32_e32 v222, v126, v191
	v_fmac_f32_e32 v223, v127, v191
	v_fmac_f32_e32 v224, v128, v191
	v_fmac_f32_e32 v225, v129, v191
	v_fmac_f32_e32 v226, v126, v207
	v_fmac_f32_e32 v227, v127, v207
	v_fmac_f32_e32 v228, v128, v207
	v_fmac_f32_e32 v229, v129, v207
	v_fmac_f32_e32 v218, v130, v176
	v_fmac_f32_e32 v219, v131, v176
	v_fmac_f32_e32 v220, v132, v176
	v_fmac_f32_e32 v221, v133, v176
	v_fmac_f32_e32 v222, v130, v192
	v_fmac_f32_e32 v223, v131, v192
	v_fmac_f32_e32 v224, v132, v192
	v_fmac_f32_e32 v225, v133, v192
	v_fmac_f32_e32 v226, v130, v208
	v_fmac_f32_e32 v227, v131, v208
	v_fmac_f32_e32 v228, v132, v208
	v_fmac_f32_e32 v229, v133, v208
	v_fmac_f32_e32 v218, v134, v177
	v_fmac_f32_e32 v219, v135, v177
	v_fmac_f32_e32 v220, v136, v177
	v_fmac_f32_e32 v221, v137, v177
	v_fmac_f32_e32 v222, v134, v193
	v_fmac_f32_e32 v223, v135, v193
	v_fmac_f32_e32 v224, v136, v193
	v_fmac_f32_e32 v225, v137, v193
	v_fmac_f32_e32 v226, v134, v209
	v_fmac_f32_e32 v227, v135, v209
	v_fmac_f32_e32 v228, v136, v209
	v_fmac_f32_e32 v229, v137, v209
	v_fmac_f32_e32 v218, v138, v178
	v_fmac_f32_e32 v219, v139, v178
	v_fmac_f32_e32 v220, v140, v178
	v_fmac_f32_e32 v221, v141, v178
	v_fmac_f32_e32 v222, v138, v194
	v_fmac_f32_e32 v223, v139, v194
	v_fmac_f32_e32 v224, v140, v194
	v_fmac_f32_e32 v225, v141, v194
	v_fmac_f32_e32 v226, v138, v210
	v_fmac_f32_e32 v227, v139, v210
	v_fmac_f32_e32 v228, v140, v210
	v_fmac_f32_e32 v229, v141, v210
	v_fmac_f32_e32 v218, v142, v179
	v_fmac_f32_e32 v219, v143, v179
	v_fmac_f32_e32 v220, v144, v179
	v_fmac_f32_e32 v221, v145, v179
	v_fmac_f32_e32 v222, v142, v195
	v_fmac_f32_e32 v223, v143, v195
	v_fmac_f32_e32 v224, v144, v195
	v_fmac_f32_e32 v225, v145, v195
	v_fmac_f32_e32 v226, v142, v211
	v_fmac_f32_e32 v227, v143, v211
	v_fmac_f32_e32 v228, v144, v211
	v_fmac_f32_e32 v229, v145, v211
	v_fmac_f32_e32 v218, v146, v180
	v_fmac_f32_e32 v219, v147, v180
	v_fmac_f32_e32 v220, v148, v180
	v_fmac_f32_e32 v221, v149, v180
	v_fmac_f32_e32 v222, v146, v196
	v_fmac_f32_e32 v223, v147, v196
	v_fmac_f32_e32 v224, v148, v196
	v_fmac_f32_e32 v225, v149, v196
	v_fmac_f32_e32 v226, v146, v212
	v_fmac_f32_e32 v227, v147, v212
	v_fmac_f32_e32 v228, v148, v212
	v_fmac_f32_e32 v229, v149, v212
	v_fmac_f32_e32 v218, v150, v181
	v_fmac_f32_e32 v219, v151, v181
	v_fmac_f32_e32 v220, v152, v181
	v_fmac_f32_e32 v221, v153, v181
	v_fmac_f32_e32 v222, v150, v197
	v_fmac_f32_e32 v223, v151, v197
	v_fmac_f32_e32 v224, v152, v197
	v_fmac_f32_e32 v225, v153, v197
	v_fmac_f32_e32 v226, v150, v213
	v_fmac_f32_e32 v227, v151, v213
	v_fmac_f32_e32 v228, v152, v213
	v_fmac_f32_e32 v229, v153, v213
	v_fmac_f32_e32 v218, v154, v182
	v_fmac_f32_e32 v219, v155, v182
	v_fmac_f32_e32 v220, v156, v182
	v_fmac_f32_e32 v221, v157, v182
	v_fmac_f32_e32 v222, v154, v198
	v_fmac_f32_e32 v223, v155, v198
	v_fmac_f32_e32 v224, v156, v198
	v_fmac_f32_e32 v225, v157, v198
	v_fmac_f32_e32 v226, v154, v214
	v_fmac_f32_e32 v227, v155, v214
	v_fmac_f32_e32 v228, v156, v214
	v_fmac_f32_e32 v229, v157, v214
	v_fmac_f32_e32 v218, v158, v183
	v_fmac_f32_e32 v219, v159, v183
	v_fmac_f32_e32 v220, v160, v183
	v_fmac_f32_e32 v221, v161, v183
	v_fmac_f32_e32 v222, v158, v199
	v_fmac_f32_e32 v223, v159, v199
	v_fmac_f32_e32 v224, v160, v199
	v_fmac_f32_e32 v225, v161, v199
	v_fmac_f32_e32 v226, v158, v215
	v_fmac_f32_e32 v227, v159, v215
	v_fmac_f32_e32 v228, v160, v215
	v_fmac_f32_e32 v229, v161, v215
	v_fmac_f32_e32 v218, v162, v184
	v_fmac_f32_e32 v219, v163, v184
	v_fmac_f32_e32 v220, v164, v184
	v_fmac_f32_e32 v221, v165, v184
	v_fmac_f32_e32 v222, v162, v200
	v_fmac_f32_e32 v223, v163, v200
	v_fmac_f32_e32 v224, v164, v200
	v_fmac_f32_e32 v225, v165, v200
	v_fmac_f32_e32 v226, v162, v216
	v_fmac_f32_e32 v227, v163, v216
	v_fmac_f32_e32 v228, v164, v216
	v_fmac_f32_e32 v229, v165, v216
	v_fmac_f32_e32 v218, v166, v185
	v_fmac_f32_e32 v219, v167, v185
	v_fmac_f32_e32 v220, v168, v185
	v_fmac_f32_e32 v221, v169, v185
	v_fmac_f32_e32 v222, v166, v201
	v_fmac_f32_e32 v223, v167, v201
	v_fmac_f32_e32 v224, v168, v201
	v_fmac_f32_e32 v225, v169, v201
	v_fmac_f32_e32 v226, v166, v217
	v_fmac_f32_e32 v227, v167, v217
	v_fmac_f32_e32 v228, v168, v217
	v_fmac_f32_e32 v229, v169, v217
	v_mul_u32_u24_e32 v20, 48, v79
	v_add_u32_e32 v20, 0xc00, v20
	ds_write_b128 v20, v[218:221]
	ds_write_b128 v20, v[222:225] offset:16
	ds_write_b128 v20, v[226:229] offset:32
.Lgemv_nofma:
	s_mov_b64 exec, s[4:5]
	s_waitcnt lgkmcnt(0)
	s_barrier
	v_lshrrev_b32_e32 v21, 2, v12
	v_mul_u32_u24_e32 v21, 48, v21
	v_and_b32_e32 v22, 3, v12
	v_lshl_add_u32 v21, v22, 2, v21
	v_lshl_add_u32 v21, v11, 4, v21
	v_add_u32_e32 v21, 0xc00, v21
	v_cmp_gt_u32_e32 vcc, 0x120, v79
	s_and_saveexec_b64 s[4:5], vcc
	s_cbranch_execz .Lgemv_nored
	ds_read_b32 v170, v21
	ds_read_b32 v171, v21 offset:1152
	ds_read_b32 v172, v21 offset:2304
	ds_read_b32 v173, v21 offset:3456
	ds_read_b32 v174, v21 offset:4608
	ds_read_b32 v175, v21 offset:5760
	ds_read_b32 v176, v21 offset:6912
	ds_read_b32 v177, v21 offset:8064
	ds_read_b32 v178, v21 offset:9216
	ds_read_b32 v179, v21 offset:10368
	ds_read_b32 v180, v21 offset:11520
	ds_read_b32 v181, v21 offset:12672
	ds_read_b32 v182, v21 offset:13824
	ds_read_b32 v183, v21 offset:14976
	ds_read_b32 v184, v21 offset:16128
	ds_read_b32 v185, v21 offset:17280
	s_cmp_eq_u32 s52, 0
	s_cselect_b32 s53, 1.0, 0
	v_mul_u32_u24_e32 v24, 0x1800, v11
	v_add_u32_e32 v24, v24, v13
	v_lshlrev_b32_e32 v24, 2, v24
	s_waitcnt lgkmcnt(0)
	v_add_f32_e32 v23, v170, v171
	v_add_f32_e32 v23, v23, v172
	v_add_f32_e32 v23, v23, v173
	v_add_f32_e32 v23, v23, v174
	v_add_f32_e32 v23, v23, v175
	v_add_f32_e32 v23, v23, v176
	v_add_f32_e32 v23, v23, v177
	v_add_f32_e32 v23, v23, v178
	v_add_f32_e32 v23, v23, v179
	v_add_f32_e32 v23, v23, v180
	v_add_f32_e32 v23, v23, v181
	v_add_f32_e32 v23, v23, v182
	v_add_f32_e32 v23, v23, v183
	v_add_f32_e32 v23, v23, v184
	v_add_f32_e32 v23, v23, v185
	v_fmac_f32_e32 v23, s53, v230
	v_cmp_gt_u32_e32 vcc, 0xc0, v79
	s_and_saveexec_b64 s[6:7], vcc
	global_atomic_add_f32 v24, v23, s[18:19]
	s_mov_b64 exec, s[6:7]
	v_cmp_le_u32_e32 vcc, 0xc0, v79
	s_movk_i32 s36, 0x800
	v_cmp_gt_u32_e64 s[8:9], s36, v13
	s_and_b64 vcc, vcc, s[8:9]
	s_and_saveexec_b64 s[6:7], vcc
	global_atomic_add_f32 v14, v23, s[16:17]
	s_mov_b64 exec, s[6:7]
.Lgemv_nored:
	s_mov_b64 exec, s[4:5]
	s_waitcnt vmcnt(0)
	s_barrier
	v_cmp_eq_u32_e32 vcc, 0, v79
	s_and_saveexec_b64 s[4:5], vcc
	v_mov_b32_e32 v25, 1
	global_atomic_add v67, v25, s[14:15]
	s_mov_b64 exec, s[4:5]
	s_mov_b64 s[6:7], s[48:49]

.LBB0_246:
	v_ashrrev_i32_e32 v3, 5, v79
	s_movk_i32 s36, 0x5ff
	v_bfe_u32 v5, v15, 4, 4
	v_cmp_lt_i32_e32 vcc, s36, v79
	v_add_u32_e32 v2, s29, v3
	v_and_b32_e32 v4, 0xf8, v15
	v_xor_b32_e32 v8, 15, v5
	s_or_b64 s[8:9], vcc, s[8:9]
	v_cmp_gt_u32_e32 vcc, s81, v2
	v_add_u32_e32 v7, 0x200, v79
	v_and_b32_e32 v3, 63, v3
	v_lshlrev_b32_e32 v66, 1, v4
	v_ashrrev_i32_e32 v4, 7, v2
	v_cndmask_b32_e32 v5, v5, v8, vcc
	v_and_b32_e32 v6, 8, v15
	v_mov_b32_e32 v79, v7
	v_lshlrev_b32_e32 v7, 3, v3
	v_lshlrev_b32_e32 v8, 4, v3
	v_ashrrev_i32_e32 v3, 31, v2
	v_mad_i32_i24 v5, v4, 17, v5
	v_lshlrev_b32_e32 v4, 10, v4
	v_and_b32_e32 v14, 64, v2
	v_lshlrev_b64 v[2:3], 9, v[2:3]
	v_mul_lo_u32 v5, v5, s86
	v_or3_b32 v4, v4, v8, v6
	v_lshl_add_u64 v[2:3], s[6:7], 0, v[2:3]
	v_add3_u32 v22, 0, v5, v7
	v_lshl_add_u32 v16, v4, 3, 0
	v_lshl_add_u64 v[20:21], v[2:3], 0, v[66:67]
	ds_read_b128 v[2:5], v16 offset:17920
	ds_read_b128 v[6:9], v16 offset:17936
	ds_read_b128 v[10:13], v16 offset:17952
	ds_read_b128 v[16:19], v16 offset:17968
	ds_read_b64 v[22:23], v22
	s_waitcnt lgkmcnt(4)
	v_mov_b32_e32 v24, v3
	v_mov_b32_e32 v25, v4
	s_waitcnt lgkmcnt(3)
	v_mov_b32_e32 v26, v7
	v_mov_b32_e32 v27, v8
	s_waitcnt lgkmcnt(2)
	v_mov_b32_e32 v28, v11
	v_mov_b32_e32 v29, v12
	s_waitcnt lgkmcnt(1)
	v_mov_b32_e32 v31, v18
	v_mov_b32_e32 v33, v4
	v_mov_b32_e32 v4, v3
	v_mov_b32_e32 v34, v5
	v_mov_b32_e32 v35, v2
	v_mov_b32_e32 v3, v8
	v_mov_b32_e32 v8, v7
	v_mov_b32_e32 v36, v9
	v_mov_b32_e32 v37, v6
	v_mov_b32_e32 v7, v12
	v_mov_b32_e32 v12, v11
	v_mov_b32_e32 v38, v13
	v_mov_b32_e32 v39, v10
	v_mov_b32_e32 v11, v18
	v_mov_b32_e32 v18, v17
	v_mov_b32_e32 v40, v19
	v_mov_b32_e32 v41, v16
	v_mov_b32_e32 v30, v17
	v_mov_b32_e32 v32, v2
	v_mov_b32_e32 v2, v6
	v_mov_b32_e32 v6, v10
	v_mov_b32_e32 v10, v16
	s_waitcnt lgkmcnt(0)
	v_pk_mul_f32 v[4:5], v[22:23], v[4:5] op_sel:[1,0]
	v_pk_mul_f32 v[16:17], v[22:23], v[34:35]
	v_pk_mul_f32 v[8:9], v[22:23], v[8:9] op_sel:[1,0]
	v_pk_mul_f32 v[34:35], v[22:23], v[36:37]
	v_pk_mul_f32 v[12:13], v[22:23], v[12:13] op_sel:[1,0]
	v_pk_mul_f32 v[36:37], v[22:23], v[38:39]
	v_pk_mul_f32 v[18:19], v[22:23], v[18:19] op_sel:[1,0]
	v_pk_mul_f32 v[38:39], v[22:23], v[40:41]
	v_pk_fma_f32 v[4:5], v[22:23], v[32:33], v[4:5] op_sel_hi:[0,1,1] neg_lo:[0,0,1] neg_hi:[0,0,1]
	v_pk_fma_f32 v[16:17], v[22:23], v[24:25], v[16:17] op_sel:[0,0,1] op_sel_hi:[1,1,0]
	v_pk_fma_f32 v[2:3], v[22:23], v[2:3], v[8:9] op_sel_hi:[0,1,1] neg_lo:[0,0,1] neg_hi:[0,0,1]
	v_pk_fma_f32 v[8:9], v[22:23], v[26:27], v[34:35] op_sel:[0,0,1] op_sel_hi:[1,1,0]
	v_pk_fma_f32 v[6:7], v[22:23], v[6:7], v[12:13] op_sel_hi:[0,1,1] neg_lo:[0,0,1] neg_hi:[0,0,1]
	v_pk_fma_f32 v[12:13], v[22:23], v[28:29], v[36:37] op_sel:[0,0,1] op_sel_hi:[1,1,0]
	v_pk_fma_f32 v[10:11], v[22:23], v[10:11], v[18:19] op_sel_hi:[0,1,1] neg_lo:[0,0,1] neg_hi:[0,0,1]
	v_pk_fma_f32 v[18:19], v[22:23], v[30:31], v[38:39] op_sel:[0,0,1] op_sel_hi:[1,1,0]
	v_cmp_eq_u32_e32 vcc, 0, v14
	v_add_u32_e32 v15, 0x1000, v15
	s_nop 0
	v_cndmask_b32_e32 v5, v17, v5, vcc
	v_cndmask_b32_e32 v4, v16, v4, vcc
	v_cndmask_b32_e32 v3, v9, v3, vcc
	v_cndmask_b32_e32 v8, v8, v2, vcc
	v_cndmask_b32_e32 v7, v13, v7, vcc
	v_cndmask_b32_e32 v6, v12, v6, vcc
	v_cndmask_b32_e32 v9, v19, v11, vcc
	v_cndmask_b32_e32 v10, v18, v10, vcc
	v_cvt_pk_bf16_f32 v2, v4, v5
	v_cvt_pk_bf16_f32 v3, v8, v3
	v_cvt_pk_bf16_f32 v4, v6, v7
	v_cvt_pk_bf16_f32 v5, v10, v9
	global_store_dwordx4 v[20:21], v[2:5], off
	s_andn2_b64 exec, exec, s[8:9]
	s_cbranch_execnz .LBB0_246
	s_branch .LBB0_30
.LBB0_251:
	v_readlane_b32 s52, v255, 14
	s_mov_b64 s[8:9], 0xb00
	s_mov_b64 s[54:55], 0x400
	s_mov_b64 s[58:59], 0
	v_readlane_b32 s53, v255, 15
